# v17 with the attention loop head aligned to a 64-byte boundary (.p2align 6)
# baseline (speedup 1.0000x reference)
; #define AT_BAR() do { __builtin_amdgcn_sched_barrier(0); asm volatile("s_waitcnt lgkmcnt(0)\n\ts_barrier" ::: "memory"); __builtin_amdgcn_sched_barrier(0); } while (0)
; __device__ __forceinline__ void attn_phase(LAS unsigned char* lds, const bf16_t* Qb, const bf16_t* Kimg, const bf16_t* Vimg, bf16_t* AB, int bid, int G, int wave_k) {
;     ...
;         int b_prev = 2 * AT_BUF, b_cur = 0, b_next = AT_BUF;
;         AT_ISSUE(0, 0); AT_ISSUE(1, AT_BUF);
;         asm volatile("s_waitcnt vmcnt(0)" ::: "memory"); AT_BAR();
;         if (grpB) AT_BAR();
;         for (int t = 0; t < 256; ++t) {
.LBB0_962:
	s_waitcnt lgkmcnt(0)
	s_barrier
	s_add_u32 s0, s0, 0x6000
	s_addc_u32 s1, s1, 0
	s_mul_i32 s16, s55, 3
	s_add_u32 s18, s18, s16
	s_addc_u32 s19, s19, 0
	s_add_u32 s20, s20, 0x9000
	s_addc_u32 s21, s21, 0
	s_mov_b32 s61, 1
	s_mov_b32 s63, 0xa000
	s_movk_i32 s62, 0x5000
	s_mov_b32 s16, 0
	v_mov_b32_e32 v65, v64
	v_mov_b32_e32 v66, v64
	v_mov_b32_e32 v67, v64
	v_mov_b32_e32 v68, v64
	v_mov_b32_e32 v69, v64
	v_mov_b32_e32 v70, v64
	v_mov_b32_e32 v71, v64
	v_mov_b32_e32 v72, v64
	v_mov_b32_e32 v73, v64
	v_mov_b32_e32 v74, v64
	v_mov_b32_e32 v75, v64
	v_mov_b32_e32 v76, v64
	v_mov_b32_e32 v77, v64
	v_mov_b32_e32 v78, v64
	v_mov_b32_e32 v79, v64
	v_mov_b32_e32 v234, v223
	v_mov_b32_e32 v237, v222
	s_mov_b32 s64, s16
	v_add_u32_e32 v160, s62, v236
	v_add_u32_e32 v128, s64, v236
	.p2align	6
